# first (prep) grid barrier tail replaced by the same fast top-counter poll as the in-loop barriers
# speedup vs baseline: 1.0886x; 1.0072x over previous
.LBB0_242:
	s_or_b64 exec, exec, s[8:9]
	v_cvt_f32_u32_e32 v5, v3
	s_waitcnt vmcnt(0)
	v_readfirstlane_b32 s6, v4
	v_sub_u32_e32 v4, 0, v3
	v_rcp_iflag_f32_e32 v5, v5
	v_add_u32_e32 v6, s6, v1
	v_mul_f32_e32 v5, 0x4f7ffffe, v5
	v_cvt_u32_f32_e32 v5, v5
	v_mul_lo_u32 v1, v4, v5
	v_mul_hi_u32 v1, v5, v1
	v_add_u32_e32 v1, v5, v1
	v_mul_hi_u32 v1, v6, v1
	v_mul_lo_u32 v4, v1, v3
	v_sub_u32_e32 v4, v6, v4
	v_add_u32_e32 v5, 1, v1
	v_cmp_ge_u32_e32 vcc, v4, v3
	s_nop 1
	v_cndmask_b32_e32 v1, v1, v5, vcc
	v_sub_u32_e32 v5, v4, v3
	v_cndmask_b32_e32 v4, v4, v5, vcc
	v_add_u32_e32 v5, 1, v1
	v_cmp_ge_u32_e32 vcc, v4, v3
	v_add_u32_e32 v4, 1, v6
	s_nop 0
	v_cndmask_b32_e32 v1, v1, v5, vcc
	v_mul_lo_u32 v5, v3, v1
	v_add_u32_e32 v3, v5, v3
	v_cmp_ne_u32_e32 vcc, v4, v3
	s_waitcnt lgkmcnt(0)
	v_add_u32_e32 v3, 1, v1
	v_mul_lo_u32 v3, v3, v2
	s_add_u32 s8, s26, 0x3400
	s_addc_u32 s9, s27, 0
	v_mov_b32_e32 v5, 0
	v_mov_b32_e32 v6, 1
	s_cbranch_vccnz .Lxb_poll_P
	buffer_wbl2 sc1
	s_waitcnt vmcnt(0)
	s_nop 4
	global_atomic_add v5, v6, s[8:9]
.Lxb_poll_P:
	s_nop 4
	buffer_inv sc1
	global_load_dword v249, v5, s[8:9] sc1
.Lxb_spin_P:
	global_load_dword v250, v5, s[8:9] sc1
	s_waitcnt vmcnt(1)
	v_cmp_lt_u32_e32 vcc, v249, v3
	s_cbranch_vccz .Lxb_done_P
	global_load_dword v249, v5, s[8:9] sc1
	s_waitcnt vmcnt(1)
	v_cmp_lt_u32_e32 vcc, v250, v3
	s_cbranch_vccz .Lxb_done_P
	s_branch .Lxb_spin_P
.Lxb_done_P:
.LBB0_276:
	s_or_b64 exec, exec, s[0:1]
	v_writelane_b32 v254, s93, 28
	s_cmp_lg_u64 s[26:27], 0
	s_waitcnt lgkmcnt(0)
	s_barrier
	s_cbranch_scc1 .LBB0_288
	v_lshrrev_b32_e32 v1, 20, v0
	v_lshrrev_b32_e32 v0, 10, v0
	v_or_b32_e32 v0, v0, v1
	s_movk_i32 s0, 0x3ff
	v_and_or_b32 v0, v0, s0, v234
	v_cmp_eq_u32_e32 vcc, 0, v0
	s_barrier
	s_and_saveexec_b64 s[0:1], vcc
	s_cbranch_execz .LBB0_287
	buffer_wbl2 sc1
	s_waitcnt vmcnt(0)
	s_load_dwordx2 s[4:5], s[34:35], 0x58
	v_mov_b32_e32 v2, 0
	s_mov_b64 s[6:7], exec
	v_mbcnt_lo_u32_b32 v1, s6, 0
	v_mbcnt_hi_u32_b32 v1, s7, v1
	s_waitcnt lgkmcnt(0)
	global_load_dword v0, v2, s[4:5] offset:40
	v_cmp_eq_u32_e32 vcc, 0, v1
	s_and_saveexec_b64 s[8:9], vcc
	s_cbranch_execz .LBB0_280
	s_bcnt1_i32_b64 s6, s[6:7]
	v_mov_b32_e32 v3, s6
	global_atomic_add v3, v2, v3, s[4:5] offset:32 sc0
